# POST mini-GEMM loads hoisted (16 A-row + 8 gain loads issued up front), phase-preserving pad
# baseline (speedup 1.0000x reference)
; #define LAS __attribute__((address_space(3)))
; #define MFMA32(a, b, c) __builtin_amdgcn_mfma_f32_32x32x16_bf16((a), (b), (c), 0, 0, 0)
; DI f32x16 zero16() { f32x16 z; for (int i = 0; i < 16; ++i) z[i] = 0.f; return z; }
; DI void post_unit(const Params& p, int l, int unit, LAS unsigned char* lds) {
;     ...
;   if (w < 4) {
;     const int tn = w & 1, part = w >> 1, r = lane & 31, h = lane >> 5;
;     const u16* wkv = (const u16*)(p.ws + WS_WKV) + (size_t)l * 128 * 128;
;     f32x16 c[2] = {zero16(), zero16()};
; #pragma unroll
;     for (int s = 0; s < 8; ++s) {
;       const bf16x8 bfr = *(const LAS bf16x8*)(At + (32 * tn + r) * 272 + (16 * s + 8 * h) * 2);
; #pragma unroll
;       for (int mt = 0; mt < 2; ++mt) { const bf16x8 afr = *(const bf16x8*)(wkv + (size_t)(part * 64 + 32 * mt + r) * 128 + 16 * s + 8 * h); c[mt] = MFMA32(afr, bfr, c[mt]); }
;     }
.LBB0_318:
	v_cmp_gt_i32_e32 vcc, 4, v24
	s_waitcnt lgkmcnt(0)
	s_barrier
	s_and_saveexec_b64 s[6:7], vcc
	s_cbranch_execz .LBB0_128
	v_ashrrev_i32_e32 v0, 1, v36
	s_movk_i32 s2, 0xffc0
	v_and_or_b32 v10, v0, s2, v25
	v_lshlrev_b32_e32 v0, 4, v34
	v_ashrrev_i32_e32 v11, 31, v10
	v_lshl_add_u64 v[12:13], s[24:25], 0, v[0:1]
	v_lshlrev_b64 v[2:3], 8, v[10:11]
	v_lshl_add_u64 v[46:47], v[12:13], 0, v[2:3]
	global_load_dwordx4 v[80:83], v[46:47], off
	global_load_dwordx4 v[84:87], v[46:47], off offset:32
	global_load_dwordx4 v[88:91], v[46:47], off offset:64
	global_load_dwordx4 v[92:95], v[46:47], off offset:96
	global_load_dwordx4 v[96:99], v[46:47], off offset:128
	global_load_dwordx4 v[100:103], v[46:47], off offset:160
	global_load_dwordx4 v[104:107], v[46:47], off offset:192
	global_load_dwordx4 v[108:111], v[46:47], off offset:224
	v_lshlrev_b32_e32 v6, 5, v24
	v_and_or_b32 v53, v6, 32, v25
	v_mul_u32_u24_e32 v6, 0x110, v53
	v_add3_u32 v35, 0, v6, v0
	v_or_b32_e32 v10, 32, v10
	v_ashrrev_i32_e32 v11, 31, v10
	v_lshlrev_b64 v[10:11], 8, v[10:11]
	v_lshl_add_u64 v[48:49], v[12:13], 0, v[10:11]
	global_load_dwordx4 v[112:115], v[48:49], off
	global_load_dwordx4 v[116:119], v[48:49], off offset:32
	global_load_dwordx4 v[120:123], v[48:49], off offset:64
	global_load_dwordx4 v[124:127], v[48:49], off offset:96
	global_load_dwordx4 v[140:143], v[48:49], off offset:128
	global_load_dwordx4 v[144:147], v[48:49], off offset:160
	global_load_dwordx4 v[148:151], v[48:49], off offset:192
	global_load_dwordx4 v[152:155], v[48:49], off offset:224
	ds_read_b128 v[156:159], v35 offset:22528
	ds_read_b128 v[160:163], v35 offset:22560
	ds_read_b128 v[164:167], v35 offset:22592
	s_movk_i32 s2, 0x7f
	v_cmp_lt_u32_e32 vcc, s2, v36
	v_lshlrev_b32_e32 v50, 2, v34
	s_waitcnt vmcnt(15) lgkmcnt(2)
	v_mfma_f32_32x32x16_bf16 v[18:33], v[80:83], v[156:159], 0
	global_load_dwordx4 v[80:83], v0, s[26:27]
	s_waitcnt vmcnt(8)
	v_mfma_f32_32x32x16_bf16 v[2:17], v[112:115], v[156:159], 0
	ds_read_b128 v[156:159], v35 offset:22624
	s_waitcnt lgkmcnt(2)
	v_mfma_f32_32x32x16_bf16 v[18:33], v[84:87], v[160:163], v[18:33]
	global_load_dwordx4 v[84:87], v0, s[26:27] offset:32
	s_waitcnt vmcnt(8)
	v_mfma_f32_32x32x16_bf16 v[2:17], v[116:119], v[160:163], v[2:17]
	ds_read_b128 v[160:163], v35 offset:22656
	s_waitcnt lgkmcnt(2)
	v_mfma_f32_32x32x16_bf16 v[18:33], v[88:91], v[164:167], v[18:33]
	global_load_dwordx4 v[88:91], v0, s[26:27] offset:64
	s_waitcnt vmcnt(8)
	v_mfma_f32_32x32x16_bf16 v[2:17], v[120:123], v[164:167], v[2:17]
	ds_read_b128 v[164:167], v35 offset:22688
	s_waitcnt lgkmcnt(2)
	v_mfma_f32_32x32x16_bf16 v[18:33], v[92:95], v[156:159], v[18:33]
	global_load_dwordx4 v[92:95], v0, s[26:27] offset:96
	s_waitcnt vmcnt(8)
	v_mfma_f32_32x32x16_bf16 v[2:17], v[124:127], v[156:159], v[2:17]
	ds_read_b128 v[156:159], v35 offset:22720
	s_waitcnt lgkmcnt(2)
	v_mfma_f32_32x32x16_bf16 v[18:33], v[96:99], v[160:163], v[18:33]
	global_load_dwordx4 v[96:99], v0, s[26:27] offset:128
	s_waitcnt vmcnt(8)
	v_mfma_f32_32x32x16_bf16 v[2:17], v[140:143], v[160:163], v[2:17]
	ds_read_b128 v[160:163], v35 offset:22752
	s_waitcnt lgkmcnt(2)
	v_mfma_f32_32x32x16_bf16 v[18:33], v[100:103], v[164:167], v[18:33]
	global_load_dwordx4 v[100:103], v0, s[26:27] offset:160
	s_waitcnt vmcnt(8)
	v_mfma_f32_32x32x16_bf16 v[2:17], v[144:147], v[164:167], v[2:17]
	s_waitcnt lgkmcnt(1)
	v_mfma_f32_32x32x16_bf16 v[18:33], v[104:107], v[156:159], v[18:33]
	global_load_dwordx4 v[104:107], v0, s[26:27] offset:192
	s_waitcnt vmcnt(8)
	v_mfma_f32_32x32x16_bf16 v[2:17], v[148:151], v[156:159], v[2:17]
	s_waitcnt lgkmcnt(0)
	v_mfma_f32_32x32x16_bf16 v[18:33], v[108:111], v[160:163], v[18:33]
	global_load_dwordx4 v[108:111], v0, s[26:27] offset:224
	s_waitcnt vmcnt(8)
	v_mfma_f32_32x32x16_bf16 v[2:17], v[152:155], v[160:163], v[2:17]
	s_and_saveexec_b64 s[2:3], vcc
	s_xor_b64 s[8:9], exec, s[2:3]
	v_mov_b32_e32 v51, v1
	s_or_saveexec_b64 s[8:9], s[8:9]
	v_mov_b64_e32 v[34:35], 64
	s_xor_b64 exec, exec, s[8:9]
	s_cbranch_execz .LBB0_127
; DI int crow(int i, int h) { return (i & 3) + 8 * (i >> 2) + 4 * h; }
; DI void post_unit(const Params& p, int l, int unit, LAS unsigned char* lds) {
;     ...
;     if (part == 0) {
;       float ss = 0.f;
; #pragma unroll
;       for (int mt = 0; mt < 2; ++mt)
; #pragma unroll
;         for (int i = 0; i < 16; ++i) ss += c[mt][i] * c[mt][i];
;       ss += __shfl_xor(ss, 32);
;       const float rs = rsqrtf(ss * (1.0f / 64.0f) + EPS); const float* kna = p.k_norm_a + l * 64;
; #pragma unroll
;       for (int mt = 0; mt < 2; ++mt)
; #pragma unroll
;         for (int i = 0; i < 16; ++i) c[mt][i] *= rs * kna[32 * mt + crow(i, h)];
; #pragma unroll
;       for (int j = 0; j < 4; ++j) { const f32x2 cv = cs16[t * 8 + 4 * h + j]; const float x1 = c[0][j], x2 = c[0][4 + j]; c[0][j] = x1 * cv[0] - x2 * cv[1]; c[0][4 + j] = x2 * cv[0] + x1 * cv[1]; }
	s_nop 1
	v_mul_f32_e32 v46, v19, v19
	v_fmac_f32_e32 v46, v18, v18
	v_fmac_f32_e32 v46, v20, v20
	v_fmac_f32_e32 v46, v21, v21
	v_fmac_f32_e32 v46, v22, v22
	v_fmac_f32_e32 v46, v23, v23
	v_fmac_f32_e32 v46, v24, v24
	v_fmac_f32_e32 v46, v25, v25
	v_fmac_f32_e32 v46, v26, v26
	v_fmac_f32_e32 v46, v27, v27
	v_fmac_f32_e32 v46, v28, v28
	v_fmac_f32_e32 v46, v29, v29
	v_fmac_f32_e32 v46, v30, v30
	v_fmac_f32_e32 v46, v31, v31
	v_fmac_f32_e32 v46, v32, v32
	v_fmac_f32_e32 v46, v33, v33
	v_fmac_f32_e32 v46, v2, v2
	v_fmac_f32_e32 v46, v3, v3
	v_fmac_f32_e32 v46, v4, v4
	v_fmac_f32_e32 v46, v5, v5
	v_fmac_f32_e32 v46, v6, v6
	v_fmac_f32_e32 v46, v7, v7
	v_pk_mul_f32 v[44:45], v[8:9], v[8:9]
	v_pk_mul_f32 v[42:43], v[10:11], v[10:11]
	v_add_f32_e32 v44, v44, v46
	v_add_f32_e32 v44, v45, v44
	v_add_f32_e32 v42, v42, v44
	v_pk_mul_f32 v[40:41], v[12:13], v[12:13]
	v_add_f32_e32 v42, v43, v42
	v_add_f32_e32 v40, v40, v42
	v_pk_mul_f32 v[38:39], v[14:15], v[14:15]
	v_add_f32_e32 v40, v41, v40
	v_add_f32_e32 v38, v38, v40
	v_pk_mul_f32 v[34:35], v[16:17], v[16:17]
	v_add_f32_e32 v38, v39, v38
	v_add_f32_e32 v34, v34, v38
	s_waitcnt vmcnt(0)
	v_mov_b64_e32 v[38:39], v[88:89]
	v_mov_b64_e32 v[40:41], v[90:91]
	v_add_f32_e32 v34, v35, v34
	ds_bpermute_b32 v35, v37, v34
	v_mov_b32_e32 v51, v1
	s_waitcnt lgkmcnt(0)
	v_add_f32_e32 v34, v34, v35
	v_fmamk_f32 v34, v34, 0x3c800000, v170
	v_cmp_gt_f32_e32 vcc, s33, v34
	v_mul_f32_e32 v35, 0x4b800000, v34
	s_nop 0
	v_cndmask_b32_e32 v34, v34, v35, vcc
	v_rsq_f32_e32 v34, v34
	s_nop 0
	v_mul_f32_e32 v35, 0x45800000, v34
	v_cndmask_b32_e32 v52, v34, v35, vcc
	v_pk_mul_f32 v[34:35], v[52:53], v[38:39] op_sel_hi:[0,1]
	v_pk_mul_f32 v[26:27], v[26:27], v[34:35]
	v_pk_mul_f32 v[34:35], v[52:53], v[40:41] op_sel_hi:[0,1]
	v_mov_b64_e32 v[38:39], v[92:93]
	v_mov_b64_e32 v[40:41], v[94:95]
	v_pk_mul_f32 v[28:29], v[28:29], v[34:35]
	v_pk_mul_f32 v[34:35], v[52:53], v[38:39] op_sel_hi:[0,1]
	v_pk_mul_f32 v[30:31], v[30:31], v[34:35]
	v_pk_mul_f32 v[34:35], v[52:53], v[40:41] op_sel_hi:[0,1]
	v_mov_b64_e32 v[38:39], v[96:97]
	v_mov_b64_e32 v[40:41], v[98:99]
	v_mov_b64_e32 v[42:43], v[100:101]
	v_mov_b64_e32 v[44:45], v[102:103]
	v_mov_b64_e32 v[46:47], v[104:105]
	v_mov_b64_e32 v[48:49], v[106:107]
	v_mov_b64_e32 v[54:55], v[108:109]
	v_mov_b64_e32 v[56:57], v[110:111]
	v_pk_mul_f32 v[32:33], v[32:33], v[34:35]
	v_pk_mul_f32 v[34:35], v[52:53], v[38:39] op_sel_hi:[0,1]
	v_pk_mul_f32 v[2:3], v[2:3], v[34:35]
	v_lshlrev_b32_e32 v34, 6, v53
	v_and_b32_e32 v35, 32, v36
	v_pk_mul_f32 v[38:39], v[52:53], v[40:41] op_sel_hi:[0,1]
	v_pk_mul_f32 v[40:41], v[52:53], v[42:43] op_sel_hi:[0,1]
	v_pk_mul_f32 v[42:43], v[52:53], v[44:45] op_sel_hi:[0,1]
	v_pk_mul_f32 v[44:45], v[52:53], v[46:47] op_sel_hi:[0,1]
	v_add3_u32 v34, 0, v34, v35
	v_pk_mul_f32 v[46:47], v[52:53], v[48:49] op_sel_hi:[0,1]
	v_pk_mul_f32 v[48:49], v[52:53], v[54:55] op_sel_hi:[0,1]
	v_pk_mul_f32 v[10:11], v[10:11], v[44:45]
	v_pk_mul_f32 v[8:9], v[8:9], v[42:43]
	v_pk_mul_f32 v[6:7], v[6:7], v[40:41]
	v_pk_mul_f32 v[4:5], v[4:5], v[38:39]
	ds_read_b128 v[38:41], v34
	ds_read_b128 v[34:37], v34 offset:16
	v_mov_b64_e32 v[42:43], v[80:81]
	v_mov_b64_e32 v[44:45], v[82:83]
	v_pk_mul_f32 v[14:15], v[14:15], v[48:49]
	v_pk_mul_f32 v[12:13], v[12:13], v[46:47]
	v_mov_b64_e32 v[46:47], v[84:85]
	v_mov_b64_e32 v[48:49], v[86:87]
	v_pk_mul_f32 v[54:55], v[52:53], v[56:57] op_sel_hi:[0,1]
	v_pk_mul_f32 v[16:17], v[16:17], v[54:55]
	v_pk_mul_f32 v[42:43], v[42:43], v[52:53] op_sel_hi:[1,0]
	s_nop 0
	v_pk_mul_f32 v[42:43], v[18:19], v[42:43]
	v_pk_mul_f32 v[18:19], v[46:47], v[52:53] op_sel_hi:[1,0]
	s_waitcnt lgkmcnt(1)
	v_mov_b32_e32 v47, v40
	v_mov_b32_e32 v40, v39
	v_pk_mul_f32 v[22:23], v[22:23], v[18:19]
	v_mov_b32_e32 v46, v38
	v_pk_mul_f32 v[38:39], v[42:43], v[40:41]
	v_pk_mul_f32 v[18:19], v[22:23], v[40:41]
	v_pk_fma_f32 v[22:23], v[22:23], v[46:47], v[38:39]
	v_pk_mul_f32 v[38:39], v[44:45], v[52:53] op_sel_hi:[1,0]
	s_waitcnt lgkmcnt(0)
	v_mov_b32_e32 v41, v36
	v_pk_mul_f32 v[38:39], v[20:21], v[38:39]
	v_pk_mul_f32 v[20:21], v[48:49], v[52:53] op_sel_hi:[1,0]
	v_mov_b32_e32 v36, v35
	v_pk_mul_f32 v[24:25], v[24:25], v[20:21]
	v_mov_b32_e32 v40, v34
	v_pk_mul_f32 v[20:21], v[24:25], v[36:37]
	v_pk_mul_f32 v[34:35], v[38:39], v[36:37]
	v_pk_fma_f32 v[18:19], v[42:43], v[46:47], v[18:19] neg_lo:[0,0,1] neg_hi:[0,0,1]
	v_pk_fma_f32 v[20:21], v[38:39], v[40:41], v[20:21] neg_lo:[0,0,1] neg_hi:[0,0,1]
	v_pk_fma_f32 v[24:25], v[24:25], v[40:41], v[34:35]
	v_mov_b64_e32 v[34:35], 0
	s_branch .LBB0_127
	s_nop 0
